# DIFF flash loop: K-frag LDS reads hoisted to tile top, V frags double-buffered, next-tile LDS staging writes interleaved with PV MFMAs
# speedup vs baseline: 1.0121x; 1.0052x over previous
.LBB0_478:
	s_and_b32 s53, s0, 1
	s_mul_i32 s1, s53, 0x2400
	v_add_u32_e32 v30, s1, v242
	ds_read_b128 v[2:5], v30
	ds_read_b128 v[6:9], v30 offset:32
	ds_read_b128 v[10:13], v30 offset:4608
	ds_read_b128 v[14:17], v30 offset:4640
	ds_read_b128 v[18:21], v30 offset:64
	ds_read_b128 v[22:25], v30 offset:96
	ds_read_b128 v[26:29], v30 offset:4672
	ds_read_b128 v[30:33], v30 offset:4704
	s_add_i32 s52, s0, 1
	s_cmp_lt_u32 s52, s49
	s_cselect_b64 s[22:23], -1, 0
	s_cmp_ge_u32 s52, s49
	s_cbranch_scc1 .LBB0_480
	v_lshl_add_u64 v[98:99], v[220:221], 0, s[96:97]
	global_load_dwordx4 v[146:149], v[98:99], off
	v_lshl_add_u64 v[98:99], v[218:219], 0, s[96:97]
	global_load_dwordx4 v[150:153], v[98:99], off
	v_lshl_add_u64 v[98:99], v[204:205], 0, s[96:97]
	global_load_dwordx4 v[154:157], v[98:99], off
	v_lshl_add_u64 v[98:99], v[206:207], 0, s[96:97]
	global_load_dwordx4 v[158:161], v[98:99], off
	v_lshl_add_u64 v[98:99], v[208:209], 0, s[96:97]
	global_load_dwordx4 v[162:165], v[98:99], off
	v_lshl_add_u64 v[98:99], v[216:217], 0, s[96:97]
	global_load_dwordx4 v[166:169], v[98:99], off
.LBB0_480:
	s_and_b32 s53, s0, 1
	s_sub_i32 s0, s51, 63
	v_or_b32_e32 v99, 31, v213
	v_cmp_le_i32_e32 vcc, s0, v99
	v_add_u32_e32 v99, 0xc0000001, v213
	v_cmp_ge_i32_e64 s[0:1], s51, v99
	s_and_b64 s[24:25], vcc, s[0:1]
	s_mov_b64 s[0:1], 0
	s_and_saveexec_b64 s[26:27], s[24:25]
	s_xor_b64 s[24:25], exec, s[26:27]
	s_cbranch_execnz .LBB0_486
	s_andn2_saveexec_b64 s[24:25], s[24:25]
	s_cbranch_execnz .LBB0_497

.LBB0_483:
	s_waitcnt lgkmcnt(0)
	s_xor_b32 s0, s53, 1
	s_mul_i32 s1, s0, 0x2400
	v_lshlrev_b32_e32 v2, 1, v239
	v_lshlrev_b32_e32 v3, 1, v186
	v_add3_u32 v2, s1, v2, v3
	s_waitcnt vmcnt(5)
	ds_write_b128 v2, v[146:149]
	v_lshlrev_b32_e32 v2, 1, v240
	v_lshlrev_b32_e32 v3, 1, v188
	s_lshl_b32 s0, s0, 13
	v_add3_u32 v2, s1, v2, v3
	s_add_i32 s1, s1, s0
	s_waitcnt vmcnt(4)
	ds_write_b128 v2, v[150:153]
	v_lshl_add_u32 v2, v236, 1, s1
	v_add3_u32 v2, v2, v0, s93
	s_waitcnt vmcnt(3)
	ds_write2_b64 v2, v[154:155], v[156:157] offset1:1
	v_lshl_add_u32 v2, v237, 1, s1
	v_add3_u32 v2, v2, v0, s93
	s_waitcnt vmcnt(2)
	ds_write2_b64 v2, v[158:159], v[160:161] offset1:1
	v_lshl_add_u32 v2, v238, 1, s1
	v_add3_u32 v2, v2, v0, s93
	s_waitcnt vmcnt(1)
	ds_write2_b64 v2, v[162:163], v[164:165] offset1:1
	v_lshl_add_u32 v2, v241, 1, s1
	v_add3_u32 v2, v2, v0, s93
	s_waitcnt vmcnt(0)
	ds_write2_b64 v2, v[166:167], v[168:169] offset1:1

.LBB0_486:
	s_brev_b32 s0, -4
	v_cmp_gt_i32_e32 vcc, s51, v213
	v_cmp_lt_i32_e64 s[0:1], s0, v244
	v_add_u32_e32 v98, 0xffffff81, v213
	s_or_b64 s[0:1], vcc, s[0:1]
	v_cmp_ge_i32_e32 vcc, s51, v98
	s_or_b64 s[26:27], s[0:1], vcc
	s_waitcnt lgkmcnt(5)
	v_mfma_f32_32x32x16_bf16 v[98:113], v[10:13], v[130:133], 0
	s_mul_i32 s0, s53, 0x4400
	v_add_u32_e32 v226, s0, v243
	v_mfma_f32_32x32x16_bf16 v[114:129], v[2:5], v[130:133], 0
	v_add_u32_e32 v2, 0x4800, v226
	ds_read2_b64 v[182:185], v2 offset1:2
	ds_read2_b64 v[178:181], v2 offset0:4 offset1:6
	ds_read2_b64 v[174:177], v2 offset0:8 offset1:10
	ds_read2_b64 v[170:173], v2 offset0:12 offset1:14
	s_waitcnt lgkmcnt(8)
	v_mfma_f32_32x32x16_bf16 v[98:113], v[14:17], v[134:137], v[98:113]
	v_mfma_f32_32x32x16_bf16 v[114:129], v[6:9], v[134:137], v[114:129]
	s_waitcnt lgkmcnt(5)
	v_mfma_f32_32x32x16_bf16 v[98:113], v[26:29], v[138:141], v[98:113]
	v_mfma_f32_32x32x16_bf16 v[114:129], v[18:21], v[138:141], v[114:129]
	s_waitcnt lgkmcnt(4)
	v_mfma_f32_32x32x16_bf16 v[98:113], v[30:33], v[142:145], v[98:113]
	v_mfma_f32_32x32x16_bf16 v[114:129], v[22:25], v[142:145], v[114:129]
	s_and_saveexec_b64 s[0:1], s[26:27]
	s_xor_b64 s[28:29], exec, s[0:1]
	s_cbranch_execz .LBB0_488
	v_add_u32_e32 v15, v245, v244
	v_subrev_u32_e32 v2, 31, v15
	v_cmp_gt_u32_e32 vcc, 2.0, v2
	v_med3_i32 v2, v2, 0, v229
	v_lshlrev_b32_e32 v2, 2, v2
	s_movk_i32 s0, 0xffe1
	ds_read_b32 v2, v2 offset:60000
	v_add3_u32 v14, v215, v244, s0
	v_sub_u32_e32 v11, v14, v187
	v_med3_i32 v3, v11, 0, v229
	v_lshlrev_b32_e32 v3, 2, v3
	ds_read_b32 v3, v3 offset:60000
	s_waitcnt lgkmcnt(1)
	v_fmac_f32_e32 v2, 0x3e38aa3b, v114
	v_cndmask_b32_e32 v114, v230, v2, vcc
	v_subrev_u32_e32 v2, 32, v15
	v_cmp_gt_u32_e32 vcc, 2.0, v2
	v_med3_i32 v2, v2, 0, v229
	v_lshlrev_b32_e32 v2, 2, v2
	ds_read_b32 v2, v2 offset:60000
	v_sub_u32_e32 v16, v14, v190
	v_cmp_gt_u32_e64 s[0:1], 2.0, v11
	v_sub_u32_e32 v13, v14, v189
	v_sub_u32_e32 v12, v14, v192
	s_waitcnt lgkmcnt(0)
	v_fmac_f32_e32 v2, 0x3e38aa3b, v115
	v_cndmask_b32_e32 v115, v230, v2, vcc
	v_med3_i32 v2, v16, 0, v229
	v_lshlrev_b32_e32 v2, 2, v2
	ds_read_b32 v2, v2 offset:60000
	v_cmp_gt_u32_e32 vcc, 2.0, v16
	v_sub_u32_e32 v9, v14, v191
	v_sub_u32_e32 v8, v14, v194
	v_sub_u32_e32 v7, v14, v193
	s_waitcnt lgkmcnt(0)
	v_pk_fma_f32 v[2:3], v[116:117], s[92:93], v[2:3] op_sel_hi:[1,0,1]
	v_sub_u32_e32 v6, v14, v196
	v_cndmask_b32_e64 v117, v230, v3, s[0:1]
	v_cndmask_b32_e32 v116, v230, v2, vcc
	v_med3_i32 v2, v12, 0, v229
	v_med3_i32 v3, v13, 0, v229
	v_lshlrev_b32_e32 v2, 2, v2
	v_lshlrev_b32_e32 v3, 2, v3
	ds_read_b32 v2, v2 offset:60000
	ds_read_b32 v3, v3 offset:60000
	v_cmp_gt_u32_e32 vcc, 2.0, v12
	v_cmp_gt_u32_e64 s[0:1], 2.0, v13
	v_max3_f32 v4, v114, s33, v115
	v_max3_f32 v4, v4, v116, v117
	s_waitcnt lgkmcnt(0)
	v_pk_fma_f32 v[2:3], v[118:119], s[92:93], v[2:3] op_sel_hi:[1,0,1]
	v_sub_u32_e32 v5, v14, v195
	v_cndmask_b32_e64 v119, v230, v3, s[0:1]
	v_cndmask_b32_e32 v118, v230, v2, vcc
	v_med3_i32 v2, v8, 0, v229
	v_med3_i32 v3, v9, 0, v229
	v_lshlrev_b32_e32 v2, 2, v2
	v_lshlrev_b32_e32 v3, 2, v3
	ds_read_b32 v2, v2 offset:60000
	ds_read_b32 v3, v3 offset:60000
	v_cmp_gt_u32_e32 vcc, 2.0, v8
	v_cmp_gt_u32_e64 s[0:1], 2.0, v9
	v_max3_f32 v4, v4, v118, v119
	s_waitcnt lgkmcnt(0)
	v_pk_fma_f32 v[2:3], v[120:121], s[92:93], v[2:3] op_sel_hi:[1,0,1]
	s_nop 0
	v_cndmask_b32_e64 v121, v230, v3, s[0:1]
	v_cndmask_b32_e32 v120, v230, v2, vcc
	v_med3_i32 v2, v6, 0, v229
	v_med3_i32 v3, v7, 0, v229
	v_lshlrev_b32_e32 v2, 2, v2
	v_lshlrev_b32_e32 v3, 2, v3
	ds_read_b32 v2, v2 offset:60000
	ds_read_b32 v3, v3 offset:60000
	v_cmp_gt_u32_e32 vcc, 2.0, v6
	v_cmp_gt_u32_e64 s[0:1], 2.0, v7
	v_max3_f32 v4, v4, v120, v121
	s_waitcnt lgkmcnt(0)
	v_pk_fma_f32 v[2:3], v[122:123], s[92:93], v[2:3] op_sel_hi:[1,0,1]
	s_nop 0
	v_cndmask_b32_e64 v123, v230, v3, s[0:1]
	v_cndmask_b32_e32 v122, v230, v2, vcc
	v_max3_f32 v10, v4, v122, v123
	v_sub_u32_e32 v4, v14, v198
	v_med3_i32 v2, v4, 0, v229
	v_med3_i32 v3, v5, 0, v229
	v_lshlrev_b32_e32 v2, 2, v2
	v_lshlrev_b32_e32 v3, 2, v3
	ds_read_b32 v2, v2 offset:60000
	ds_read_b32 v3, v3 offset:60000
	v_cmp_gt_u32_e32 vcc, 2.0, v4
	v_cmp_gt_u32_e64 s[0:1], 2.0, v5
	s_waitcnt lgkmcnt(0)
	v_pk_fma_f32 v[2:3], v[124:125], s[92:93], v[2:3] op_sel_hi:[1,0,1]
	s_nop 0
	v_cndmask_b32_e32 v124, v230, v2, vcc
	v_sub_u32_e32 v2, v14, v200
	v_med3_i32 v17, v2, 0, v229
	v_cndmask_b32_e64 v125, v230, v3, s[0:1]
	v_sub_u32_e32 v3, v14, v197
	v_lshlrev_b32_e32 v17, 2, v17
	ds_read_b32 v18, v17 offset:60000
	v_med3_i32 v17, v3, 0, v229
	v_lshlrev_b32_e32 v17, 2, v17
	ds_read_b32 v19, v17 offset:60000
	v_cmp_gt_u32_e32 vcc, 2.0, v2
	v_cmp_gt_u32_e64 s[0:1], 2.0, v3
	v_max3_f32 v10, v10, v124, v125
	s_waitcnt lgkmcnt(0)
	v_pk_fma_f32 v[18:19], v[126:127], s[92:93], v[18:19] op_sel_hi:[1,0,1]
	s_nop 0
	v_cndmask_b32_e64 v127, v230, v19, s[0:1]
	v_cndmask_b32_e32 v126, v230, v18, vcc
	v_max3_f32 v17, v10, v126, v127
	v_sub_u32_e32 v10, v14, v202
	v_sub_u32_e32 v14, v14, v199
	v_med3_i32 v18, v10, 0, v229
	v_med3_i32 v19, v14, 0, v229
	v_lshlrev_b32_e32 v18, 2, v18
	v_lshlrev_b32_e32 v19, 2, v19
	ds_read_b32 v18, v18 offset:60000
	ds_read_b32 v19, v19 offset:60000
	v_cmp_gt_u32_e32 vcc, 2.0, v10
	v_cmp_gt_u32_e64 s[0:1], 2.0, v14
	s_waitcnt lgkmcnt(0)
	v_pk_fma_f32 v[18:19], v[128:129], s[92:93], v[18:19] op_sel_hi:[1,0,1]
	s_nop 0
	v_cndmask_b32_e64 v129, v230, v19, s[0:1]
	v_cndmask_b32_e32 v128, v230, v18, vcc
	v_max3_f32 v20, v17, v128, v129
	v_subrev_u32_e32 v17, 63, v15
	v_cmp_gt_u32_e32 vcc, 2.0, v17
	v_med3_i32 v17, v17, 0, v229
	v_lshlrev_b32_e32 v17, 2, v17
	ds_read_b32 v17, v17 offset:60000
	v_subrev_u32_e32 v15, 64, v15
	v_cmp_gt_u32_e64 s[0:1], 2.0, v15
	v_mov_b32_e32 v18, v99
	v_mov_b32_e32 v19, v100
	s_waitcnt lgkmcnt(0)
	v_fmac_f32_e32 v17, 0x3e38aa3b, v98
	v_cndmask_b32_e32 v98, v230, v17, vcc
	v_subrev_u32_e32 v17, 32, v16
	v_med3_i32 v16, v15, 0, v229
	v_med3_i32 v15, v17, 0, v229
	v_lshlrev_b32_e32 v16, 2, v16
	v_lshlrev_b32_e32 v15, 2, v15
	ds_read_b32 v16, v16 offset:60000
	v_cmp_gt_u32_e32 vcc, 2.0, v17
	ds_read_b32 v17, v15 offset:60000
	s_waitcnt lgkmcnt(0)
	v_pk_fma_f32 v[16:17], v[18:19], s[92:93], v[16:17] op_sel_hi:[1,0,1]
	s_nop 0
	v_cndmask_b32_e32 v100, v230, v17, vcc
	v_cndmask_b32_e64 v99, v230, v16, s[0:1]
	v_pk_mov_b32 v[16:17], v[10:11], v[12:13] op_sel:[1,0]
	v_mov_b32_e32 v18, v101
	v_subrev_u32_e32 v11, 32, v17
	v_subrev_u32_e32 v17, 32, v16
	v_med3_i32 v16, v17, 0, v229
	v_cmp_gt_u32_e64 s[0:1], 2.0, v11
	v_med3_i32 v11, v11, 0, v229
	v_lshlrev_b32_e32 v16, 2, v16
	v_lshlrev_b32_e32 v11, 2, v11
	ds_read_b32 v16, v16 offset:60000
	v_cmp_gt_u32_e32 vcc, 2.0, v17
	ds_read_b32 v17, v11 offset:60000
	v_mov_b32_e32 v19, v102
	v_max3_f32 v15, v20, v98, v99
	v_pk_mov_b32 v[12:13], v[12:13], v[8:9] op_sel:[1,0]
	v_pk_mov_b32 v[8:9], v[8:9], v[6:7] op_sel:[1,0]
	s_waitcnt lgkmcnt(0)
	v_pk_fma_f32 v[16:17], v[18:19], s[92:93], v[16:17] op_sel_hi:[1,0,1]
	v_subrev_u32_e32 v13, 32, v13
	v_cndmask_b32_e32 v101, v230, v16, vcc
	v_max3_f32 v11, v15, v100, v101
	v_subrev_u32_e32 v15, 32, v12
	v_cndmask_b32_e64 v102, v230, v17, s[0:1]
	v_med3_i32 v12, v15, 0, v229
	v_cmp_gt_u32_e64 s[0:1], 2.0, v13
	v_med3_i32 v13, v13, 0, v229
	v_lshlrev_b32_e32 v12, 2, v12
	v_lshlrev_b32_e32 v13, 2, v13
	ds_read_b32 v12, v12 offset:60000
	ds_read_b32 v13, v13 offset:60000
	v_mov_b32_e32 v16, v103
	v_mov_b32_e32 v17, v104
	v_cmp_gt_u32_e32 vcc, 2.0, v15
	v_subrev_u32_e32 v9, 32, v9
	s_waitcnt lgkmcnt(0)
	v_pk_fma_f32 v[12:13], v[16:17], s[92:93], v[12:13] op_sel_hi:[1,0,1]
	v_pk_mov_b32 v[6:7], v[6:7], v[4:5] op_sel:[1,0]
	v_cndmask_b32_e32 v103, v230, v12, vcc
	v_subrev_u32_e32 v12, 32, v8
	v_cndmask_b32_e64 v104, v230, v13, s[0:1]
	v_med3_i32 v8, v12, 0, v229
	v_cmp_gt_u32_e64 s[0:1], 2.0, v9
	v_med3_i32 v9, v9, 0, v229
	v_lshlrev_b32_e32 v8, 2, v8
	v_lshlrev_b32_e32 v9, 2, v9
	ds_read_b32 v8, v8 offset:60000
	ds_read_b32 v9, v9 offset:60000
	v_cmp_gt_u32_e32 vcc, 2.0, v12
	v_mov_b32_e32 v12, v105
	v_mov_b32_e32 v13, v106
	v_subrev_u32_e32 v7, 32, v7
	s_waitcnt lgkmcnt(0)
	v_pk_fma_f32 v[8:9], v[12:13], s[92:93], v[8:9] op_sel_hi:[1,0,1]
	v_pk_mov_b32 v[4:5], v[4:5], v[2:3] op_sel:[1,0]
	v_cndmask_b32_e32 v105, v230, v8, vcc
	v_subrev_u32_e32 v8, 32, v6
	v_cndmask_b32_e64 v106, v230, v9, s[0:1]
	v_med3_i32 v6, v8, 0, v229
	v_cmp_gt_u32_e64 s[0:1], 2.0, v7
	v_med3_i32 v7, v7, 0, v229
	v_lshlrev_b32_e32 v6, 2, v6
	v_lshlrev_b32_e32 v7, 2, v7
	ds_read_b32 v6, v6 offset:60000
	ds_read_b32 v7, v7 offset:60000
	v_cmp_gt_u32_e32 vcc, 2.0, v8
	v_mov_b32_e32 v8, v107
	v_mov_b32_e32 v9, v108
	v_subrev_u32_e32 v5, 32, v5
	s_waitcnt lgkmcnt(0)
	v_pk_fma_f32 v[6:7], v[8:9], s[92:93], v[6:7] op_sel_hi:[1,0,1]
	v_max3_f32 v11, v11, v102, v103
	v_cndmask_b32_e32 v107, v230, v6, vcc
	v_subrev_u32_e32 v6, 32, v4
	v_cndmask_b32_e64 v108, v230, v7, s[0:1]
	v_med3_i32 v4, v6, 0, v229
	v_cmp_gt_u32_e64 s[0:1], 2.0, v5
	v_med3_i32 v5, v5, 0, v229
	v_lshlrev_b32_e32 v4, 2, v4
	v_lshlrev_b32_e32 v5, 2, v5
	ds_read_b32 v4, v4 offset:60000
	ds_read_b32 v5, v5 offset:60000
	v_max3_f32 v11, v11, v104, v105
	v_cmp_gt_u32_e32 vcc, 2.0, v6
	v_mov_b32_e32 v6, v109
	v_mov_b32_e32 v7, v110
	s_waitcnt lgkmcnt(0)
	v_pk_fma_f32 v[4:5], v[6:7], s[92:93], v[4:5] op_sel_hi:[1,0,1]
	v_pk_mov_b32 v[2:3], v[2:3], v[10:11] op_sel:[1,0]
	v_cndmask_b32_e32 v109, v230, v4, vcc
	v_subrev_u32_e32 v3, 32, v3
	v_subrev_u32_e32 v4, 32, v2
	v_cndmask_b32_e64 v110, v230, v5, s[0:1]
	v_med3_i32 v2, v4, 0, v229
	v_cmp_gt_u32_e64 s[0:1], 2.0, v3
	v_med3_i32 v3, v3, 0, v229
	v_lshlrev_b32_e32 v2, 2, v2
	v_lshlrev_b32_e32 v3, 2, v3
	ds_read_b32 v2, v2 offset:60000
	ds_read_b32 v3, v3 offset:60000
	v_cmp_gt_u32_e32 vcc, 2.0, v4
	v_mov_b32_e32 v4, v111
	v_mov_b32_e32 v5, v112
	v_max3_f32 v8, v11, v106, v107
	s_waitcnt lgkmcnt(0)
	v_pk_fma_f32 v[2:3], v[4:5], s[92:93], v[2:3] op_sel_hi:[1,0,1]
	v_max3_f32 v6, v8, v108, v109
	v_cndmask_b32_e64 v112, v230, v3, s[0:1]
	v_subrev_u32_e32 v3, 32, v14
	v_cndmask_b32_e32 v111, v230, v2, vcc
	v_cmp_gt_u32_e32 vcc, 2.0, v3
	v_med3_i32 v3, v3, 0, v229
	v_lshlrev_b32_e32 v3, 2, v3
	ds_read_b32 v3, v3 offset:60000
	v_max3_f32 v2, v6, v110, v111
	s_waitcnt lgkmcnt(0)
	v_fmac_f32_e32 v3, 0x3e38aa3b, v113
	v_cndmask_b32_e32 v113, v230, v3, vcc
	v_max3_f32 v2, v2, v112, v113

.LBB0_496:
	s_or_b64 exec, exec, s[0:1]
	v_cvt_pk_bf16_f32 v2, v2, v3
	v_cvt_pk_bf16_f32 v3, v4, v5
	v_cvt_pk_bf16_f32 v4, v6, v7
	v_cvt_pk_bf16_f32 v5, v8, v9
	v_cvt_pk_bf16_f32 v6, v10, v11
	v_cvt_pk_bf16_f32 v7, v12, v13
	v_mfma_f32_32x32x16_bf16 v[82:97], v[182:185], v[2:5], v[82:97]
	v_cvt_pk_bf16_f32 v8, v14, v15
	v_cvt_pk_bf16_f32 v9, v16, v17
	v_cvt_pk_bf16_f32 v10, v18, v19
	v_cvt_pk_bf16_f32 v11, v20, v21
	v_cvt_pk_bf16_f32 v12, v22, v23
	v_cvt_pk_bf16_f32 v13, v24, v25
	v_exp_f32_e32 v33, v33
	v_mfma_f32_32x32x16_bf16 v[82:97], v[178:181], v[6:9], v[82:97]
	v_cvt_pk_bf16_f32 v14, v26, v27
	v_cvt_pk_bf16_f32 v15, v28, v29
	v_cvt_pk_bf16_f32 v16, v30, v31
	v_cvt_pk_bf16_f32 v17, v32, v33
	v_add_u32_e32 v30, 0x5800, v226
	v_add_f32_e32 v98, v33, v248
	ds_read2_b64 v[18:21], v30 offset0:32 offset1:34
	ds_read2_b64 v[22:25], v30 offset0:36 offset1:38
	ds_read2_b64 v[26:29], v30 offset0:40 offset1:42
	ds_read2_b64 v[30:33], v30 offset0:44 offset1:46
	v_mfma_f32_32x32x16_bf16 v[82:97], v[174:177], v[10:13], v[82:97]
	v_add_f32_e32 v203, v203, v98
	v_mfma_f32_32x32x16_bf16 v[82:97], v[170:173], v[14:17], v[82:97]
	v_add_u32_e32 v98, 0x6800, v226
	ds_read2_b64 v[182:185], v98 offset0:64 offset1:66
	ds_read2_b64 v[178:181], v98 offset0:68 offset1:70
	ds_read2_b64 v[174:177], v98 offset0:72 offset1:74
	ds_read2_b64 v[170:173], v98 offset0:76 offset1:78
	s_waitcnt lgkmcnt(7)
	v_mfma_f32_32x32x16_bf16 v[66:81], v[18:21], v[2:5], v[66:81]
	s_xor_b32 s0, s53, 1
	s_mul_i32 s1, s0, 0x2400
	v_lshlrev_b32_e32 v100, 1, v239
	v_lshlrev_b32_e32 v101, 1, v186
	v_add3_u32 v100, s1, v100, v101
	s_waitcnt vmcnt(5)
	ds_write_b128 v100, v[146:149]
	s_waitcnt lgkmcnt(7)
	v_mfma_f32_32x32x16_bf16 v[66:81], v[22:25], v[6:9], v[66:81]
	v_lshlrev_b32_e32 v100, 1, v240
	v_lshlrev_b32_e32 v101, 1, v188
	s_lshl_b32 s0, s0, 13
	v_add3_u32 v100, s1, v100, v101
	s_add_i32 s1, s1, s0
	s_waitcnt vmcnt(4)
	ds_write_b128 v100, v[150:153]
	s_waitcnt lgkmcnt(7)
	v_mfma_f32_32x32x16_bf16 v[66:81], v[26:29], v[10:13], v[66:81]
	v_lshl_add_u32 v100, v236, 1, s1
	v_add3_u32 v100, v100, v0, s93
	s_waitcnt vmcnt(3)
	ds_write2_b64 v100, v[154:155], v[156:157] offset1:1
	s_waitcnt lgkmcnt(7)
	v_mfma_f32_32x32x16_bf16 v[66:81], v[30:33], v[14:17], v[66:81]
	v_add_u32_e32 v98, 0x7800, v226
	ds_read2_b64 v[18:21], v98 offset0:96 offset1:98
	ds_read2_b64 v[22:25], v98 offset0:100 offset1:102
	ds_read2_b64 v[26:29], v98 offset0:104 offset1:106
	ds_read2_b64 v[30:33], v98 offset0:108 offset1:110
	s_waitcnt lgkmcnt(10)
	v_mfma_f32_32x32x16_bf16 v[50:65], v[182:185], v[2:5], v[50:65]
	v_lshl_add_u32 v100, v237, 1, s1
	v_add3_u32 v100, v100, v0, s93
	s_waitcnt vmcnt(2)
	ds_write2_b64 v100, v[158:159], v[160:161] offset1:1
	s_waitcnt lgkmcnt(10)
	v_mfma_f32_32x32x16_bf16 v[50:65], v[178:181], v[6:9], v[50:65]
	v_lshl_add_u32 v100, v238, 1, s1
	v_add3_u32 v100, v100, v0, s93
	s_waitcnt vmcnt(1)
	ds_write2_b64 v100, v[162:163], v[164:165] offset1:1
	s_waitcnt lgkmcnt(10)
	v_mfma_f32_32x32x16_bf16 v[50:65], v[174:177], v[10:13], v[50:65]
	v_lshl_add_u32 v100, v241, 1, s1
	v_add3_u32 v100, v100, v0, s93
	s_waitcnt vmcnt(0)
	ds_write2_b64 v100, v[166:167], v[168:169] offset1:1
	s_waitcnt lgkmcnt(10)
	v_mfma_f32_32x32x16_bf16 v[50:65], v[170:173], v[14:17], v[50:65]
	s_waitcnt lgkmcnt(6)
	v_mfma_f32_32x32x16_bf16 v[34:49], v[18:21], v[2:5], v[34:49]
	s_waitcnt lgkmcnt(5)
	v_mfma_f32_32x32x16_bf16 v[34:49], v[22:25], v[6:9], v[34:49]
	s_waitcnt lgkmcnt(4)
	v_mfma_f32_32x32x16_bf16 v[34:49], v[26:29], v[10:13], v[34:49]
	s_waitcnt lgkmcnt(3)
	v_mfma_f32_32x32x16_bf16 v[34:49], v[30:33], v[14:17], v[34:49]
	s_mov_b64 s[0:1], 0
	s_andn2_saveexec_b64 s[24:25], s[24:25]
	s_cbranch_execz .LBB0_482
